# GLA: next-chunk global loads issued at start of the q/k scaling stage (k loads to spare regs, copied at latch), chunk-start wait relaxed to vmcnt(4) so output stores drain in the background
# baseline (speedup 1.0000x reference)
.LBB0_533:
	s_or_b64 exec, exec, s[10:11]
	v_cmp_gt_i32_e32 vcc, 64, v2
	v_lshlrev_b32_e32 v129, 2, v2
	s_and_saveexec_b64 s[10:11], vcc
	ds_write_b32 v129, v179 offset:23552
	s_or_b64 exec, exec, s[10:11]
	s_add_u32 s58, s2, 0x22622100
	s_addc_u32 s59, s3, 0
	s_ashr_i32 s54, s95, 2
	v_lshlrev_b32_e32 v25, 3, v8
	s_add_u32 s56, s2, 0x18e80000
	v_and_b32_e32 v3, 24, v25
	s_addc_u32 s57, s3, 0
	s_ashr_i32 s55, s54, 31
	v_mul_u32_u24_e32 v3, 0x480, v3
	s_mul_i32 s10, s54, 0x480000
	v_add3_u32 v178, v0, s5, v3
	s_mul_hi_i32 s5, s54, 0x480000
	s_add_u32 s12, s58, s10
	s_addc_u32 s13, s59, s5
	v_lshl_add_u64 v[4:5], v[178:179], 1, s[12:13]
	v_add_u32_e32 v72, 0xc0, v178
	v_mov_b32_e32 v73, v179
	v_add_u32_e32 v74, 0x480, v178
	v_mov_b32_e32 v75, v179
	v_add_u32_e32 v76, 0x540, v178
	v_mov_b32_e32 v77, v179
	v_add_u32_e32 v78, 0x900, v178
	v_mov_b32_e32 v79, v179
	v_add_u32_e32 v80, 0x9c0, v178
	v_mov_b32_e32 v81, v179
	v_add_u32_e32 v82, 0xd80, v178
	v_mov_b32_e32 v83, v179
	v_add_u32_e32 v84, 0xe40, v178
	v_mov_b32_e32 v85, v179
	v_add_u32_e32 v86, 0x1200, v178
	v_mov_b32_e32 v87, v179
	v_mul_hi_u32 v3, v2, s87
	v_lshl_add_u64 v[6:7], v[72:73], 1, s[12:13]
	v_lshl_add_u64 v[12:13], v[74:75], 1, s[12:13]
	v_lshl_add_u64 v[14:15], v[76:77], 1, s[12:13]
	v_lshl_add_u64 v[16:17], v[78:79], 1, s[12:13]
	v_lshl_add_u64 v[18:19], v[80:81], 1, s[12:13]
	v_lshl_add_u64 v[20:21], v[82:83], 1, s[12:13]
	v_lshl_add_u64 v[22:23], v[84:85], 1, s[12:13]
	global_load_ushort v26, v[4:5], off
	global_load_ushort v143, v[6:7], off
	global_load_ushort v27, v[12:13], off
	global_load_ushort v140, v[14:15], off
	global_load_ushort v28, v[16:17], off
	global_load_ushort v136, v[18:19], off
	global_load_ushort v29, v[20:21], off
	global_load_ushort v138, v[22:23], off
	v_lshl_add_u64 v[4:5], v[86:87], 1, s[12:13]
	v_add_u32_e32 v88, 0x12c0, v178
	v_mov_b32_e32 v89, v179
	v_add_u32_e32 v90, 0x1680, v178
	v_mov_b32_e32 v91, v179
	v_add_u32_e32 v92, 0x1740, v178
	v_mov_b32_e32 v93, v179
	v_add_u32_e32 v94, 0x1b00, v178
	v_mov_b32_e32 v95, v179
	v_add_u32_e32 v96, 0x1bc0, v178
	v_mov_b32_e32 v97, v179
	v_add_u32_e32 v98, 0x1f80, v178
	v_mov_b32_e32 v99, v179
	v_add_u32_e32 v100, 0x2040, v178
	v_mov_b32_e32 v101, v179
	v_lshrrev_b32_e32 v3, 6, v3
	v_lshl_add_u64 v[6:7], v[88:89], 1, s[12:13]
	v_lshl_add_u64 v[12:13], v[90:91], 1, s[12:13]
	v_lshl_add_u64 v[14:15], v[92:93], 1, s[12:13]
	v_lshl_add_u64 v[16:17], v[94:95], 1, s[12:13]
	v_lshl_add_u64 v[18:19], v[96:97], 1, s[12:13]
	v_lshl_add_u64 v[20:21], v[98:99], 1, s[12:13]
	v_lshl_add_u64 v[22:23], v[100:101], 1, s[12:13]
	global_load_ushort v30, v[4:5], off
	global_load_ushort v144, v[6:7], off
	global_load_ushort v31, v[12:13], off
	global_load_ushort v142, v[14:15], off
	global_load_ushort v32, v[16:17], off
	global_load_ushort v137, v[18:19], off
	global_load_ushort v33, v[20:21], off
	global_load_ushort v139, v[22:23], off
	s_mul_i32 s5, s4, 0x60
	v_mul_lo_u32 v4, v3, s86
	v_mul_lo_u32 v3, v3, s75
	s_addk_i32 s5, 0x180
	v_sub_u32_e32 v3, v2, v3
	v_add_u32_e32 v34, 0x100, v2
	v_add3_u32 v102, v3, s5, v4
	v_mul_hi_u32 v3, v34, s87
	v_lshrrev_b32_e32 v3, 6, v3
	v_mul_lo_u32 v6, v3, s86
	v_mul_lo_u32 v3, v3, s75
	v_sub_u32_e32 v3, v34, v3
	v_add_u32_e32 v35, 0x200, v2
	v_add3_u32 v104, v3, s5, v6
	v_mul_hi_u32 v3, v35, s87
	v_lshrrev_b32_e32 v3, 6, v3
	v_mul_lo_u32 v12, v3, s86
	v_mul_lo_u32 v3, v3, s75
	v_sub_u32_e32 v3, v35, v3
	v_add_u32_e32 v36, 0x300, v2
	v_add3_u32 v106, v3, s5, v12
	v_mul_hi_u32 v3, v36, s87
	v_lshrrev_b32_e32 v3, 6, v3
	v_mul_lo_u32 v14, v3, s86
	v_mul_lo_u32 v3, v3, s75
	v_sub_u32_e32 v3, v36, v3
	v_add_u32_e32 v37, 0x400, v2
	v_add3_u32 v108, v3, s5, v14
	v_mul_hi_u32 v3, v37, s87
	v_lshrrev_b32_e32 v3, 6, v3
	v_mul_lo_u32 v16, v3, s86
	v_mul_lo_u32 v3, v3, s75
	v_sub_u32_e32 v3, v37, v3
	v_add_u32_e32 v38, 0x500, v2
	v_add3_u32 v110, v3, s5, v16
	v_mul_hi_u32 v3, v38, s87
	v_lshrrev_b32_e32 v3, 6, v3
	v_mul_lo_u32 v18, v3, s86
	v_mul_lo_u32 v3, v3, s75
	v_sub_u32_e32 v3, v38, v3
	v_add_u32_e32 v39, 0x600, v2
	v_add3_u32 v112, v3, s5, v18
	v_mul_hi_u32 v3, v39, s87
	v_lshrrev_b32_e32 v3, 6, v3
	v_mul_lo_u32 v20, v3, s86
	v_mul_lo_u32 v3, v3, s75
	v_sub_u32_e32 v3, v39, v3
	v_add_u32_e32 v40, 0x700, v2
	v_add3_u32 v114, v3, s5, v20
	v_mul_hi_u32 v3, v40, s87
	v_lshrrev_b32_e32 v3, 6, v3
	v_mul_lo_u32 v22, v3, s86
	v_mul_lo_u32 v3, v3, s75
	v_mov_b32_e32 v103, v179
	v_mov_b32_e32 v111, v179
	v_sub_u32_e32 v3, v40, v3
	v_lshl_add_u64 v[4:5], v[102:103], 1, s[12:13]
	v_mov_b32_e32 v105, v179
	v_mov_b32_e32 v107, v179
	v_mov_b32_e32 v109, v179
	v_lshl_add_u64 v[16:17], v[110:111], 1, s[12:13]
	v_mov_b32_e32 v113, v179
	v_mov_b32_e32 v115, v179
	v_add3_u32 v116, v3, s5, v22
	v_mov_b32_e32 v117, v179
	v_lshl_add_u64 v[6:7], v[104:105], 1, s[12:13]
	v_lshl_add_u64 v[12:13], v[106:107], 1, s[12:13]
	v_lshl_add_u64 v[14:15], v[108:109], 1, s[12:13]
	v_lshl_add_u64 v[18:19], v[112:113], 1, s[12:13]
	v_lshl_add_u64 v[20:21], v[114:115], 1, s[12:13]
	v_lshl_add_u64 v[22:23], v[116:117], 1, s[12:13]
	global_load_ushort v181, v[4:5], off
	global_load_ushort v182, v[6:7], off
	global_load_ushort v183, v[12:13], off
	global_load_ushort v184, v[14:15], off
	global_load_ushort v185, v[16:17], off
	global_load_ushort v186, v[18:19], off
	global_load_ushort v187, v[20:21], off
	global_load_ushort v188, v[22:23], off
	v_add_u32_e32 v16, 0x800, v2
	v_mul_hi_u32 v3, v16, s87
	v_lshrrev_b32_e32 v3, 6, v3
	v_mul_lo_u32 v4, v3, s86
	v_mul_lo_u32 v3, v3, s75
	v_sub_u32_e32 v3, v16, v3
	v_add_u32_e32 v17, 0x900, v2
	v_add3_u32 v118, v3, s5, v4
	v_mul_hi_u32 v3, v17, s87
	v_lshrrev_b32_e32 v3, 6, v3
	v_mul_lo_u32 v6, v3, s86
	v_mul_lo_u32 v3, v3, s75
	v_sub_u32_e32 v3, v17, v3
	v_add_u32_e32 v18, 0xa00, v2
	v_add3_u32 v120, v3, s5, v6
	v_mul_hi_u32 v3, v18, s87
	v_lshrrev_b32_e32 v3, 6, v3
	v_mul_lo_u32 v12, v3, s86
	v_mul_lo_u32 v3, v3, s75
	v_sub_u32_e32 v3, v18, v3
	v_add_u32_e32 v19, 0xb00, v2
	v_add3_u32 v122, v3, s5, v12
	v_mul_hi_u32 v3, v19, s87
	v_lshrrev_b32_e32 v3, 6, v3
	v_mul_lo_u32 v14, v3, s86
	v_mul_lo_u32 v3, v3, s75
	s_lshl_b64 s[10:11], s[54:55], 17
	s_lshl_b64 s[52:53], s[54:55], 11
	v_mov_b32_e32 v119, v179
	v_sub_u32_e32 v3, v19, v3
	v_lshl_add_u64 v[4:5], v[118:119], 1, s[12:13]
	v_mov_b32_e32 v121, v179
	v_mov_b32_e32 v123, v179
	v_add3_u32 v124, v3, s5, v14
	v_mov_b32_e32 v125, v179
	s_add_u32 s10, s56, s10
	v_ashrrev_i32_e32 v3, 31, v2
	v_lshl_add_u64 v[6:7], v[120:121], 1, s[12:13]
	v_lshl_add_u64 v[12:13], v[122:123], 1, s[12:13]
	v_lshl_add_u64 v[14:15], v[124:125], 1, s[12:13]
	global_load_ushort v189, v[4:5], off
	global_load_ushort v190, v[6:7], off
	global_load_ushort v191, v[12:13], off
	global_load_ushort v192, v[14:15], off
	s_addc_u32 s11, s57, s11
	v_lshlrev_b64 v[4:5], 2, v[2:3]
	v_add_u32_e32 v3, 47, v2
	v_lshl_add_u64 v[6:7], s[10:11], 0, v[4:5]
	v_lshlrev_b32_e32 v126, 2, v0
	v_cmp_gt_u32_e64 s[16:17], s67, v3
	v_and_b32_e32 v3, 0x7ffffff3, v0
	v_and_b32_e32 v1, 31, v2
	v_bfe_u32 v11, v2, 5, 1
	global_load_dword v193, v[6:7], off
	global_load_dword v194, v[6:7], off offset:1024
	v_and_b32_e32 v6, 16, v126
	v_lshlrev_b32_e32 v3, 1, v3
	v_and_b32_e32 v7, 8, v0
	v_ashrrev_i32_e32 v24, 6, v2
	s_movk_i32 s5, 0x8f
	v_or3_b32 v3, v6, v3, v7
	v_mul_u32_u24_e32 v6, 56, v1
	v_lshlrev_b32_e32 v128, 4, v11
	v_cmp_lt_i32_e64 s[14:15], s5, v2
	s_movk_i32 s5, 0x4c
	v_lshl_add_u32 v145, v6, 1, v128
	v_lshlrev_b32_e32 v6, 5, v24
	v_ashrrev_i32_e32 v9, 4, v9
	s_waitcnt vmcnt(30)
	v_mad_u64_u32 v[12:13], s[18:19], v0, s5, v[126:127]
	v_or_b32_e32 v7, v6, v1
	v_add_u32_e32 v9, v9, v10
	v_mad_u64_u32 v[130:131], s[18:19], v7, s74, v[128:129]
	v_lshlrev_b32_e32 v13, 5, v1
	v_mul_lo_u32 v10, v9, s75
	v_cmp_lt_i32_e64 s[10:11], 47, v2
	v_cmp_lt_i32_e64 s[12:13], s67, v2
	v_sub_u32_e32 v131, v145, v13
	v_sub_u32_e32 v2, v2, v10
	v_and_b32_e32 v10, 0x7ffffff3, v9
	v_lshlrev_b32_e32 v13, 2, v9
	v_mul_lo_u32 v2, v2, s74
	v_and_b32_e32 v13, 16, v13
	v_lshlrev_b32_e32 v10, 1, v10
	v_add3_u32 v2, v2, v13, v10
	v_and_or_b32 v146, v9, 8, v2
	v_mul_hi_i32 v2, v34, s79
	v_lshrrev_b32_e32 v9, 31, v2
	v_ashrrev_i32_e32 v2, 4, v2
	v_add_u32_e32 v2, v2, v9
	v_mul_lo_u32 v9, v2, s75
	v_sub_u32_e32 v9, v34, v9
	v_and_b32_e32 v10, 0x7ffffff3, v2
	v_lshlrev_b32_e32 v13, 2, v2
	v_mul_lo_u32 v9, v9, s74
	v_and_b32_e32 v13, 16, v13
	v_lshlrev_b32_e32 v10, 1, v10
	v_add3_u32 v9, v9, v13, v10
	v_and_or_b32 v148, v2, 8, v9
	v_mul_hi_i32 v2, v35, s79
	v_lshrrev_b32_e32 v9, 31, v2
	v_ashrrev_i32_e32 v2, 4, v2
	v_add_u32_e32 v2, v2, v9
	v_mul_lo_u32 v9, v2, s75
	v_sub_u32_e32 v9, v35, v9
	v_and_b32_e32 v10, 0x7ffffff3, v2
	v_lshlrev_b32_e32 v13, 2, v2
	v_mul_lo_u32 v9, v9, s74
	v_and_b32_e32 v13, 16, v13
	v_lshlrev_b32_e32 v10, 1, v10
	v_add3_u32 v9, v9, v13, v10
	v_and_or_b32 v149, v2, 8, v9
	v_mul_hi_i32 v2, v36, s79
	v_lshrrev_b32_e32 v9, 31, v2
	v_ashrrev_i32_e32 v2, 4, v2
	v_add_u32_e32 v2, v2, v9
	v_mul_lo_u32 v9, v2, s75
	v_sub_u32_e32 v9, v36, v9
	v_and_b32_e32 v10, 0x7ffffff3, v2
	v_lshlrev_b32_e32 v13, 2, v2
	v_mul_lo_u32 v9, v9, s74
	v_and_b32_e32 v13, 16, v13
	v_lshlrev_b32_e32 v10, 1, v10
	v_add3_u32 v9, v9, v13, v10
	v_and_or_b32 v150, v2, 8, v9
	v_mul_hi_i32 v2, v37, s79
	v_lshrrev_b32_e32 v9, 31, v2
	v_ashrrev_i32_e32 v2, 4, v2
	v_add_u32_e32 v2, v2, v9
	v_mul_lo_u32 v9, v2, s75
	v_sub_u32_e32 v9, v37, v9
	v_and_b32_e32 v10, 0x7ffffff3, v2
	v_lshlrev_b32_e32 v13, 2, v2
	v_mul_lo_u32 v9, v9, s74
	v_and_b32_e32 v13, 16, v13
	v_lshlrev_b32_e32 v10, 1, v10
	v_add3_u32 v9, v9, v13, v10
	v_and_or_b32 v151, v2, 8, v9
	v_mul_hi_i32 v2, v38, s79
	v_lshrrev_b32_e32 v9, 31, v2
	v_ashrrev_i32_e32 v2, 4, v2
	v_add_u32_e32 v2, v2, v9
	v_mul_lo_u32 v9, v2, s75
	v_sub_u32_e32 v9, v38, v9
	v_and_b32_e32 v10, 0x7ffffff3, v2
	v_lshlrev_b32_e32 v13, 2, v2
	v_mul_lo_u32 v9, v9, s74
	v_and_b32_e32 v13, 16, v13
	v_lshlrev_b32_e32 v10, 1, v10
	v_add3_u32 v9, v9, v13, v10
	v_and_or_b32 v152, v2, 8, v9
	v_mul_hi_i32 v2, v39, s79
	v_lshrrev_b32_e32 v9, 31, v2
	v_ashrrev_i32_e32 v2, 4, v2
	v_add_u32_e32 v2, v2, v9
	v_mul_lo_u32 v9, v2, s75
	v_sub_u32_e32 v9, v39, v9
	v_and_b32_e32 v10, 0x7ffffff3, v2
	v_lshlrev_b32_e32 v13, 2, v2
	v_mul_lo_u32 v9, v9, s74
	v_and_b32_e32 v13, 16, v13
	v_lshlrev_b32_e32 v10, 1, v10
	v_add3_u32 v9, v9, v13, v10
	v_and_or_b32 v153, v2, 8, v9
	v_mul_hi_i32 v2, v40, s79
	v_lshrrev_b32_e32 v9, 31, v2
	v_ashrrev_i32_e32 v2, 4, v2
	v_add_u32_e32 v2, v2, v9
	v_mul_lo_u32 v9, v2, s75
	v_sub_u32_e32 v9, v40, v9
	v_and_b32_e32 v10, 0x7ffffff3, v2
	v_lshlrev_b32_e32 v13, 2, v2
	v_mul_lo_u32 v9, v9, s74
	v_and_b32_e32 v13, 16, v13
	v_lshlrev_b32_e32 v10, 1, v10
	v_add3_u32 v9, v9, v13, v10
	v_and_or_b32 v154, v2, 8, v9
	v_mul_hi_i32 v2, v16, s79
	v_lshrrev_b32_e32 v9, 31, v2
	v_ashrrev_i32_e32 v2, 4, v2
	v_add_u32_e32 v2, v2, v9
	v_mul_lo_u32 v9, v2, s75
	v_sub_u32_e32 v9, v16, v9
	v_and_b32_e32 v10, 0x7ffffff3, v2
	v_lshlrev_b32_e32 v13, 2, v2
	v_mul_lo_u32 v9, v9, s74
	v_and_b32_e32 v13, 16, v13
	v_lshlrev_b32_e32 v10, 1, v10
	v_add3_u32 v9, v9, v13, v10
	v_and_or_b32 v155, v2, 8, v9
	v_mul_hi_i32 v2, v17, s79
	v_lshrrev_b32_e32 v9, 31, v2
	v_ashrrev_i32_e32 v2, 4, v2
	v_add_u32_e32 v2, v2, v9
	v_mul_lo_u32 v9, v2, s75
	v_sub_u32_e32 v9, v17, v9
	v_and_b32_e32 v10, 0x7ffffff3, v2
	v_lshlrev_b32_e32 v13, 2, v2
	v_mul_lo_u32 v9, v9, s74
	v_and_b32_e32 v13, 16, v13
	v_lshlrev_b32_e32 v10, 1, v10
	v_add3_u32 v9, v9, v13, v10
	v_and_or_b32 v156, v2, 8, v9
	v_mul_hi_i32 v2, v18, s79
	v_lshrrev_b32_e32 v9, 31, v2
	v_ashrrev_i32_e32 v2, 4, v2
	v_add_u32_e32 v2, v2, v9
	v_mul_lo_u32 v9, v2, s75
	v_sub_u32_e32 v9, v18, v9
	v_and_b32_e32 v10, 0x7ffffff3, v2
	v_lshlrev_b32_e32 v13, 2, v2
	v_mul_lo_u32 v9, v9, s74
	v_and_b32_e32 v13, 16, v13
	v_lshlrev_b32_e32 v10, 1, v10
	v_add3_u32 v9, v9, v13, v10
	v_and_or_b32 v157, v2, 8, v9
	v_mul_hi_i32 v2, v19, s79
	v_lshrrev_b32_e32 v9, 31, v2
	v_ashrrev_i32_e32 v2, 4, v2
	v_add_u32_e32 v2, v2, v9
	v_mul_lo_u32 v9, v2, s75
	v_sub_u32_e32 v9, v19, v9
	v_and_b32_e32 v10, 0x7ffffff3, v2
	v_lshlrev_b32_e32 v13, 2, v2
	v_mul_lo_u32 v9, v9, s74
	v_and_b32_e32 v13, 16, v13
	v_lshlrev_b32_e32 v10, 1, v10
	v_add3_u32 v9, v9, v13, v10
	s_movk_i32 s5, 0x1c0
	v_and_or_b32 v158, v2, 8, v9
	v_mul_lo_u32 v2, v8, s5
	v_add_lshl_u32 v159, v2, v0, 1
	v_lshl_add_u32 v160, v2, 1, v3
	v_lshlrev_b32_e32 v2, 4, v8
	v_lshlrev_b32_e32 v141, 9, v8
	v_and_b32_e32 v2, 0xffffffe0, v2
	v_and_b32_e32 v8, 8, v25
	s_mov_b32 s5, 0x7ffffff1
	v_add3_u32 v161, v12, v2, v8
	v_or_b32_e32 v2, 1, v25
	v_bitop3_b32 v9, v25, s5, 1 bitop3:0xc8
	v_mul_lo_u32 v2, v2, 56
	v_lshlrev_b32_e32 v9, 1, v9
	v_add3_u32 v164, v12, v9, v8
	v_add_u32_e32 v9, 56, v2
	s_mov_b32 s5, 0x7ffffff2
	v_add_lshl_u32 v165, v9, v0, 1
	v_lshl_add_u32 v166, v9, 1, v3
	v_bitop3_b32 v9, v25, s5, 2 bitop3:0xc8
	v_lshlrev_b32_e32 v9, 1, v9
	v_add3_u32 v167, v12, v9, v8
	v_add_u32_e32 v9, 0x70, v2
	s_mov_b32 s5, 0x7ffffff3
	v_add_lshl_u32 v168, v9, v0, 1
	v_lshl_add_u32 v169, v9, 1, v3
	v_bitop3_b32 v9, v25, s5, 3 bitop3:0xc8
	v_lshlrev_b32_e32 v9, 1, v9
	v_add3_u32 v170, v12, v9, v8
	v_add_u32_e32 v8, 0xe0, v2
	v_lshlrev_b32_e32 v11, 2, v11
	v_add_lshl_u32 v162, v2, v0, 1
	v_lshl_add_u32 v163, v2, 1, v3
	v_add_lshl_u32 v171, v8, v0, 1
	v_lshl_add_u32 v172, v8, 1, v3
	v_add_u32_e32 v8, 0x118, v2
	v_add_u32_e32 v2, 0x150, v2
	v_add_lshl_u32 v173, v8, v0, 1
	v_add_lshl_u32 v175, v2, v0, 1
	v_or_b32_e32 v0, 2, v11
	v_cmp_gt_u32_e64 s[22:23], v0, v1
	v_or_b32_e32 v0, 3, v11
	v_cmp_gt_u32_e64 s[24:25], v0, v1
	v_or_b32_e32 v0, 8, v11
	v_cmp_gt_u32_e64 s[26:27], v0, v1
	v_or_b32_e32 v0, 9, v11
	v_cmp_gt_u32_e64 s[28:29], v0, v1
	v_or_b32_e32 v0, 10, v11
	v_cmp_gt_u32_e64 s[30:31], v0, v1
	v_or_b32_e32 v0, 11, v11
	v_cmp_gt_u32_e64 s[34:35], v0, v1
	v_or_b32_e32 v0, 16, v11
	v_cmp_gt_u32_e64 s[36:37], v0, v1
	v_or_b32_e32 v0, 17, v11
	v_cmp_gt_u32_e64 s[38:39], v0, v1
	v_or_b32_e32 v0, 18, v11
	v_cmp_gt_u32_e64 s[40:41], v0, v1
	v_or_b32_e32 v0, 19, v11
	v_cmp_gt_u32_e64 s[42:43], v0, v1
	v_or_b32_e32 v0, 24, v11
	v_cmp_gt_u32_e64 s[44:45], v0, v1
	v_or_b32_e32 v0, 25, v11
	v_cmp_gt_u32_e64 s[46:47], v0, v1
	v_or_b32_e32 v0, 26, v11
	v_cmp_gt_u32_e64 s[48:49], v0, v1
	v_or_b32_e32 v0, 27, v11
	v_lshl_add_u32 v180, v2, 1, v3
	v_cmp_gt_u32_e64 s[50:51], v0, v1
	s_mul_hi_i32 s5, s54, 0x300000
	s_mul_i32 s54, s54, 0x300000
	v_mul_hi_u32_u24_e32 v0, 0x600, v1
	v_mul_u32_u24_e32 v2, 0x600, v1
	v_cmp_gt_u32_e64 s[18:19], v11, v1
	v_cmp_lt_u32_e64 s[20:21], v11, v1
	v_or_b32_e32 v1, s5, v0
	v_or_b32_e32 v0, s54, v2
	v_mad_u64_u32 v[0:1], s[4:5], s4, v231, v[0:1]
	v_ashrrev_i32_e32 v7, 31, v6
	v_or_b32_e32 v0, v0, v128
	v_lshl_add_u64 v[0:1], v[6:7], 2, v[0:1]
	v_lshl_add_u64 v[0:1], s[2:3], 0, v[0:1]
	s_mov_b64 s[2:3], 0x26e22140
	v_mov_b32_e32 v14, v179
	v_mov_b32_e32 v15, v179
	v_cmp_gt_i32_e32 vcc, 3, v24
	v_lshl_add_u32 v174, v8, 1, v3
	s_waitcnt vmcnt(27)
	v_perm_b32 v39, v27, v26, s76
	s_waitcnt vmcnt(23)
	v_perm_b32 v38, v29, v28, s76
	s_waitcnt vmcnt(19)
	v_perm_b32 v37, v31, v30, s76
	v_lshl_add_u64 v[132:133], s[56:57], 0, v[4:5]
	v_lshl_add_u64 v[134:135], v[0:1], 0, s[2:3]
	v_mov_b32_e32 v0, v179
	v_mov_b32_e32 v1, v179
	v_mov_b32_e32 v2, v179
	v_mov_b32_e32 v3, v179
	v_mov_b32_e32 v4, v179
	v_mov_b32_e32 v5, v179
	v_mov_b32_e32 v6, v179
	v_mov_b32_e32 v7, v179
	v_mov_b32_e32 v8, v179
	v_mov_b32_e32 v9, v179
	v_mov_b32_e32 v10, v179
	v_mov_b32_e32 v11, v179
	v_mov_b32_e32 v12, v179
	v_mov_b32_e32 v13, v179
	v_mov_b64_e32 v[30:31], v[14:15]
	s_waitcnt vmcnt(15)
	v_perm_b32 v36, v33, v32, s76
	s_mov_b32 s56, 32
	v_mov_b64_e32 v[28:29], v[12:13]
	v_mov_b64_e32 v[26:27], v[10:11]
	v_mov_b64_e32 v[24:25], v[8:9]
	v_mov_b64_e32 v[22:23], v[6:7]
	v_mov_b64_e32 v[20:21], v[4:5]
	v_mov_b64_e32 v[18:19], v[2:3]
	v_mov_b64_e32 v[16:17], v[0:1]
	v_lshlrev_b32_e32 v72, 1, v72
	v_lshlrev_b32_e32 v73, 1, v74
	v_lshlrev_b32_e32 v74, 1, v76
	v_lshlrev_b32_e32 v75, 1, v78
	v_lshlrev_b32_e32 v76, 1, v80
	v_lshlrev_b32_e32 v77, 1, v82
	v_lshlrev_b32_e32 v78, 1, v84
	v_lshlrev_b32_e32 v79, 1, v86
	v_lshlrev_b32_e32 v80, 1, v88
	v_lshlrev_b32_e32 v81, 1, v90
	v_lshlrev_b32_e32 v82, 1, v92
	v_lshlrev_b32_e32 v83, 1, v94
	v_lshlrev_b32_e32 v84, 1, v96
	v_lshlrev_b32_e32 v85, 1, v98
	v_lshlrev_b32_e32 v86, 1, v100
	v_lshlrev_b32_e32 v87, 1, v102
	v_lshlrev_b32_e32 v88, 1, v104
	v_lshlrev_b32_e32 v89, 1, v106
	v_lshlrev_b32_e32 v90, 1, v108
	v_lshlrev_b32_e32 v91, 1, v110
	v_lshlrev_b32_e32 v92, 1, v112
	v_lshlrev_b32_e32 v93, 1, v114
	v_lshlrev_b32_e32 v94, 1, v116
	v_lshlrev_b32_e32 v95, 1, v118
	v_lshlrev_b32_e32 v96, 1, v120
	v_lshlrev_b32_e32 v97, 1, v122
	v_lshlrev_b32_e32 v98, 1, v124
	s_waitcnt vmcnt(0)
	s_branch .LBB0_537
.LBB0_536:
	s_or_b64 exec, exec, s[2:3]
	s_add_i32 s56, s56, 32
	s_mov_b64 s[2:3], 0xc000
	s_waitcnt vmcnt(27)
	v_perm_b32 v39, v196, v195, s76
	s_waitcnt vmcnt(23)
	v_perm_b32 v38, v198, v197, s76
	s_waitcnt vmcnt(19)
	v_perm_b32 v37, v200, v199, s76
	s_waitcnt vmcnt(15)
	v_perm_b32 v36, v202, v201, s76
	s_waitcnt vmcnt(14)
	v_mov_b32_e32 v143, v124
	v_mov_b32_e32 v140, v125
	v_mov_b32_e32 v136, v99
	v_mov_b32_e32 v138, v203
	v_mov_b32_e32 v144, v226
	v_mov_b32_e32 v142, v227
	v_mov_b32_e32 v137, v252
	v_mov_b32_e32 v139, v253
	s_cmpk_lg_i32 s56, 0x820
	v_lshl_add_u64 v[134:135], v[134:135], 0, s[2:3]
	s_barrier
	s_cbranch_scc0 .LBB0_430
.LBB0_537:
	v_mov_b32_e32 v40, 0
	v_mov_b32_e32 v41, 0
	v_mov_b32_e32 v42, 0
	v_mov_b32_e32 v43, 0
	v_mov_b32_e32 v44, 0
	v_mov_b32_e32 v45, 0
	v_mov_b32_e32 v46, 0
	v_mov_b32_e32 v47, 0
	s_waitcnt vmcnt(4)
	ds_write2st64_b32 v129, v193, v194 offset0:96 offset1:100
	ds_write_b16 v146, v181 offset:15872
	ds_write_b16 v148, v182 offset:15872
	ds_write_b16 v149, v183 offset:15872
	ds_write_b16 v150, v184 offset:15872
	ds_write_b16 v151, v185 offset:15872
	ds_write_b16 v152, v186 offset:15872
	ds_write_b16 v153, v187 offset:15872
	ds_write_b16 v154, v188 offset:15872
	ds_write_b16 v155, v189 offset:15872
	ds_write_b16 v156, v190 offset:15872
	ds_write_b16 v157, v191 offset:15872
	ds_write_b16 v158, v192 offset:15872
	s_waitcnt lgkmcnt(0)
	s_barrier
	s_and_saveexec_b64 s[2:3], s[8:9]
	s_cbranch_execz .LBB0_539
	s_mov_b32 s4, 0xbd800000
	ds_read_b128 v[32:35], v141 offset:24576
	ds_read_b128 v[48:51], v141 offset:24592
	ds_read_b128 v[182:185], v141 offset:24608
	ds_read_b128 v[186:189], v141 offset:24624
	ds_read_b128 v[190:193], v141 offset:24640
	ds_read_b128 v[194:197], v141 offset:24656
	s_waitcnt lgkmcnt(4)
	v_fma_f32 v52, v32, v58, v127
	v_mul_f32_e32 v53, v33, v56
	v_fmac_f32_e32 v52, v34, v62
	v_fmac_f32_e32 v53, v35, v60
	v_fmac_f32_e32 v52, v48, v59
	v_fmac_f32_e32 v53, v49, v57
	v_fmac_f32_e32 v52, v50, v63
	v_fmac_f32_e32 v53, v51, v61
	ds_read_b128 v[32:35], v141 offset:24672
	ds_read_b128 v[48:51], v141 offset:24688
	s_waitcnt lgkmcnt(4)
	v_fmac_f32_e32 v52, v182, v66
	v_fmac_f32_e32 v53, v183, v64
	v_fmac_f32_e32 v52, v184, v70
	v_fmac_f32_e32 v53, v185, v68
	v_fmac_f32_e32 v52, v186, v67
	v_fmac_f32_e32 v53, v187, v65
	v_fmac_f32_e32 v52, v188, v71
	v_fmac_f32_e32 v53, v189, v69
	ds_read_b128 v[182:185], v141 offset:24704
	ds_read_b128 v[186:189], v141 offset:24720
	v_add_f32_e32 v200, v52, v53
	v_mul_f32_e32 v200, 0xbfb8aa3b, v200
	v_exp_f32_e32 v200, v200
	s_waitcnt lgkmcnt(4)
	v_fma_f32 v198, v190, v58, v127
	v_mul_f32_e32 v199, v191, v56
	v_fmac_f32_e32 v198, v192, v62
	v_fmac_f32_e32 v199, v193, v60
	v_fmac_f32_e32 v198, v194, v59
	v_fmac_f32_e32 v199, v195, v57
	v_fmac_f32_e32 v198, v196, v63
	v_fmac_f32_e32 v199, v197, v61
	ds_read_b128 v[190:193], v141 offset:24736
	ds_read_b128 v[194:197], v141 offset:24752
	v_add_f32_e32 v200, 1.0, v200
	v_log_f32_e32 v200, v200
	s_waitcnt lgkmcnt(4)
	v_fmac_f32_e32 v198, v32, v66
	v_fmac_f32_e32 v199, v33, v64
	v_fmac_f32_e32 v198, v34, v70
	v_fmac_f32_e32 v199, v35, v68
	v_fmac_f32_e32 v198, v48, v67
	v_fmac_f32_e32 v199, v49, v65
	v_fmac_f32_e32 v198, v50, v71
	v_fmac_f32_e32 v199, v51, v69
	ds_read_b128 v[32:35], v141 offset:24768
	ds_read_b128 v[48:51], v141 offset:24784
	v_mul_f32_e32 v40, 0xbd800000, v200
	v_add_f32_e32 v201, v198, v199
	v_mul_f32_e32 v201, 0xbfb8aa3b, v201
	v_exp_f32_e32 v201, v201
	s_waitcnt lgkmcnt(4)
	v_fma_f32 v52, v182, v58, v127
	v_mul_f32_e32 v53, v183, v56
	v_fmac_f32_e32 v52, v184, v62
	v_fmac_f32_e32 v53, v185, v60
	v_fmac_f32_e32 v52, v186, v59
	v_fmac_f32_e32 v53, v187, v57
	v_fmac_f32_e32 v52, v188, v63
	v_fmac_f32_e32 v53, v189, v61
	ds_read_b128 v[182:185], v141 offset:24800
	ds_read_b128 v[186:189], v141 offset:24816
	v_add_f32_e32 v201, 1.0, v201
	v_log_f32_e32 v201, v201
	s_waitcnt lgkmcnt(4)
	v_fmac_f32_e32 v52, v190, v66
	v_fmac_f32_e32 v53, v191, v64
	v_fmac_f32_e32 v52, v192, v70
	v_fmac_f32_e32 v53, v193, v68
	v_fmac_f32_e32 v52, v194, v67
	v_fmac_f32_e32 v53, v195, v65
	v_fmac_f32_e32 v52, v196, v71
	v_fmac_f32_e32 v53, v197, v69
	ds_read_b128 v[190:193], v141 offset:24832
	ds_read_b128 v[194:197], v141 offset:24848
	v_fmamk_f32 v41, v201, 0xbd800000, v40
	v_add_f32_e32 v200, v52, v53
	v_mul_f32_e32 v200, 0xbfb8aa3b, v200
	v_exp_f32_e32 v200, v200
	s_waitcnt lgkmcnt(4)
	v_fma_f32 v198, v32, v58, v127
	v_mul_f32_e32 v199, v33, v56
	v_fmac_f32_e32 v198, v34, v62
	v_fmac_f32_e32 v199, v35, v60
	v_fmac_f32_e32 v198, v48, v59
	v_fmac_f32_e32 v199, v49, v57
	v_fmac_f32_e32 v198, v50, v63
	v_fmac_f32_e32 v199, v51, v61
	ds_read_b128 v[32:35], v141 offset:24864
	ds_read_b128 v[48:51], v141 offset:24880
	v_add_f32_e32 v200, 1.0, v200
	v_log_f32_e32 v200, v200
	s_waitcnt lgkmcnt(4)
	v_fmac_f32_e32 v198, v182, v66
	v_fmac_f32_e32 v199, v183, v64
	v_fmac_f32_e32 v198, v184, v70
	v_fmac_f32_e32 v199, v185, v68
	v_fmac_f32_e32 v198, v186, v67
	v_fmac_f32_e32 v199, v187, v65
	v_fmac_f32_e32 v198, v188, v71
	v_fmac_f32_e32 v199, v189, v69
	ds_read_b128 v[182:185], v141 offset:24896
	ds_read_b128 v[186:189], v141 offset:24912
	v_fmamk_f32 v42, v200, 0xbd800000, v41
	v_add_f32_e32 v201, v198, v199
	v_mul_f32_e32 v201, 0xbfb8aa3b, v201
	v_exp_f32_e32 v201, v201
	s_waitcnt lgkmcnt(4)
	v_fma_f32 v52, v190, v58, v127
	v_mul_f32_e32 v53, v191, v56
	v_fmac_f32_e32 v52, v192, v62
	v_fmac_f32_e32 v53, v193, v60
	v_fmac_f32_e32 v52, v194, v59
	v_fmac_f32_e32 v53, v195, v57
	v_fmac_f32_e32 v52, v196, v63
	v_fmac_f32_e32 v53, v197, v61
	ds_read_b128 v[190:193], v141 offset:24928
	ds_read_b128 v[194:197], v141 offset:24944
	v_add_f32_e32 v201, 1.0, v201
	v_log_f32_e32 v201, v201
	s_waitcnt lgkmcnt(4)
	v_fmac_f32_e32 v52, v32, v66
	v_fmac_f32_e32 v53, v33, v64
	v_fmac_f32_e32 v52, v34, v70
	v_fmac_f32_e32 v53, v35, v68
	v_fmac_f32_e32 v52, v48, v67
	v_fmac_f32_e32 v53, v49, v65
	v_fmac_f32_e32 v52, v50, v71
	v_fmac_f32_e32 v53, v51, v69
	ds_read_b128 v[32:35], v141 offset:24960
	ds_read_b128 v[48:51], v141 offset:24976
	v_fmamk_f32 v43, v201, 0xbd800000, v42
	v_add_f32_e32 v200, v52, v53
	v_mul_f32_e32 v200, 0xbfb8aa3b, v200
	v_exp_f32_e32 v200, v200
	s_waitcnt lgkmcnt(4)
	v_fma_f32 v198, v182, v58, v127
	v_mul_f32_e32 v199, v183, v56
	v_fmac_f32_e32 v198, v184, v62
	v_fmac_f32_e32 v199, v185, v60
	v_fmac_f32_e32 v198, v186, v59
	v_fmac_f32_e32 v199, v187, v57
	v_fmac_f32_e32 v198, v188, v63
	v_fmac_f32_e32 v199, v189, v61
	ds_read_b128 v[182:185], v141 offset:24992
	ds_read_b128 v[186:189], v141 offset:25008
	v_add_f32_e32 v200, 1.0, v200
	v_log_f32_e32 v200, v200
	s_waitcnt lgkmcnt(4)
	v_fmac_f32_e32 v198, v190, v66
	v_fmac_f32_e32 v199, v191, v64
	v_fmac_f32_e32 v198, v192, v70
	v_fmac_f32_e32 v199, v193, v68
	v_fmac_f32_e32 v198, v194, v67
	v_fmac_f32_e32 v199, v195, v65
	v_fmac_f32_e32 v198, v196, v71
	v_fmac_f32_e32 v199, v197, v69
	ds_read_b128 v[190:193], v141 offset:25024
	ds_read_b128 v[194:197], v141 offset:25040
	v_fmamk_f32 v44, v200, 0xbd800000, v43
	v_add_f32_e32 v201, v198, v199
	v_mul_f32_e32 v201, 0xbfb8aa3b, v201
	v_exp_f32_e32 v201, v201
	s_waitcnt lgkmcnt(4)
	v_fma_f32 v52, v32, v58, v127
	v_mul_f32_e32 v53, v33, v56
	v_fmac_f32_e32 v52, v34, v62
	v_fmac_f32_e32 v53, v35, v60
	v_fmac_f32_e32 v52, v48, v59
	v_fmac_f32_e32 v53, v49, v57
	v_fmac_f32_e32 v52, v50, v63
	v_fmac_f32_e32 v53, v51, v61
	ds_read_b128 v[32:35], v141 offset:25056
	ds_read_b128 v[48:51], v141 offset:25072
	v_add_f32_e32 v201, 1.0, v201
	v_log_f32_e32 v201, v201
	s_waitcnt lgkmcnt(4)
	v_fmac_f32_e32 v52, v182, v66
	v_fmac_f32_e32 v53, v183, v64
	v_fmac_f32_e32 v52, v184, v70
	v_fmac_f32_e32 v53, v185, v68
	v_fmac_f32_e32 v52, v186, v67
	v_fmac_f32_e32 v53, v187, v65
	v_fmac_f32_e32 v52, v188, v71
	v_fmac_f32_e32 v53, v189, v69
	v_fmamk_f32 v45, v201, 0xbd800000, v44
	v_add_f32_e32 v200, v52, v53
	v_mul_f32_e32 v200, 0xbfb8aa3b, v200
	v_exp_f32_e32 v200, v200
	s_waitcnt lgkmcnt(2)
	v_fma_f32 v198, v190, v58, v127
	v_mul_f32_e32 v199, v191, v56
	v_fmac_f32_e32 v198, v192, v62
	v_fmac_f32_e32 v199, v193, v60
	v_fmac_f32_e32 v198, v194, v59
	v_fmac_f32_e32 v199, v195, v57
	v_fmac_f32_e32 v198, v196, v63
	v_fmac_f32_e32 v199, v197, v61
	v_add_f32_e32 v200, 1.0, v200
	v_log_f32_e32 v200, v200
	s_waitcnt lgkmcnt(0)
	v_fmac_f32_e32 v198, v32, v66
	v_fmac_f32_e32 v199, v33, v64
	v_fmac_f32_e32 v198, v34, v70
	v_fmac_f32_e32 v199, v35, v68
	v_fmac_f32_e32 v198, v48, v67
	v_fmac_f32_e32 v199, v49, v65
	v_fmac_f32_e32 v198, v50, v71
	v_fmac_f32_e32 v199, v51, v69
	v_fmamk_f32 v46, v200, 0xbd800000, v45
	v_add_f32_e32 v201, v198, v199
	v_mul_f32_e32 v201, 0xbfb8aa3b, v201
	v_exp_f32_e32 v201, v201
	s_nop 0
	v_add_f32_e32 v201, 1.0, v201
	v_log_f32_e32 v201, v201
	s_nop 0
	v_fmamk_f32 v47, v201, 0xbd800000, v46
	ds_write_b32 v129, v47 offset:23808
.LBB0_539:
	s_or_b64 exec, exec, s[2:3]
	s_waitcnt lgkmcnt(0)
	s_barrier
	s_cmpk_lg_i32 s56, 0x800
	s_cselect_b32 s2, s56, 0x7e0
	s_add_u32 s2, s52, s2
	s_addc_u32 s3, s53, 0
	s_mul_i32 s4, s3, 0x900
	s_mul_hi_u32 s5, s2, 0x900
	s_add_i32 s5, s5, s4
	s_mul_i32 s4, s2, 0x900
	s_add_u32 s54, s58, s4
	s_addc_u32 s55, s59, s5
	v_lshl_add_u64 v[32:33], v[178:179], 1, s[54:55]
	global_load_ushort v195, v[32:33], off
	global_load_ushort v124, v72, s[54:55]
	global_load_ushort v196, v73, s[54:55]
	global_load_ushort v125, v74, s[54:55]
	global_load_ushort v197, v75, s[54:55]
	global_load_ushort v99, v76, s[54:55]
	global_load_ushort v198, v77, s[54:55]
	global_load_ushort v203, v78, s[54:55]
	global_load_ushort v199, v79, s[54:55]
	global_load_ushort v226, v80, s[54:55]
	global_load_ushort v200, v81, s[54:55]
	global_load_ushort v227, v82, s[54:55]
	global_load_ushort v201, v83, s[54:55]
	global_load_ushort v252, v84, s[54:55]
	global_load_ushort v202, v85, s[54:55]
	global_load_ushort v253, v86, s[54:55]
	global_load_ushort v181, v87, s[54:55]
	global_load_ushort v182, v88, s[54:55]
	global_load_ushort v183, v89, s[54:55]
	global_load_ushort v184, v90, s[54:55]
	global_load_ushort v185, v91, s[54:55]
	global_load_ushort v186, v92, s[54:55]
	global_load_ushort v187, v93, s[54:55]
	global_load_ushort v188, v94, s[54:55]
	global_load_ushort v189, v95, s[54:55]
	global_load_ushort v190, v96, s[54:55]
	s_lshl_b64 s[2:3], s[2:3], 6
	global_load_ushort v191, v97, s[54:55]
	global_load_ushort v192, v98, s[54:55]
	v_lshl_add_u64 v[32:33], v[132:133], 0, s[2:3]
	global_load_dword v193, v[32:33], off
	global_load_dword v194, v[32:33], off offset:1024
	s_and_saveexec_b64 s[2:3], s[8:9]
	s_cbranch_execz .LBB0_543
	v_add_u32_e32 v32, 0x5c00, v126
	ds_read2_b32 v[34:35], v32 offset0:64 offset1:112
	ds_read2_b32 v[32:33], v32 offset0:160 offset1:208
	s_waitcnt lgkmcnt(1)
	v_add_f32_e32 v48, v34, v35
	s_waitcnt lgkmcnt(0)
	v_add_f32_e32 v33, v32, v33
	v_add_f32_e32 v33, v48, v33
	s_and_saveexec_b64 s[54:55], s[16:17]
	v_exp_f32_e32 v48, v33
	ds_write_b32 v126, v48 offset:23552
	s_or_b64 exec, exec, s[54:55]
	v_cndmask_b32_e64 v34, 0, v34, s[10:11]
	v_cndmask_b32_e64 v35, 0, v35, s[12:13]
	v_add_f32_e32 v34, v34, v35
	v_cndmask_b32_e64 v32, 0, v32, s[14:15]
	v_add_f32_e32 v32, v34, v32
	v_add_f32_e32 v34, v40, v32
	v_exp_f32_e32 v35, v34
	v_lshlrev_b32_e32 v40, 16, v39
	v_mul_f32_e32 v40, 0x3e13cd3a, v40
	v_lshlrev_b32_e32 v48, 16, v143
	v_mul_f32_e32 v35, v40, v35
	v_exp_f32_e64 v40, -v34
	v_sub_f32_e32 v34, v33, v34
	v_exp_f32_e32 v34, v34
	v_cvt_pk_bf16_f32 v35, v35, s0
	ds_write_b16 v159, v35
	ds_write_b16 v160, v35 offset:3584
	v_mul_f32_e32 v35, v40, v48
	v_mul_f32_e32 v34, v34, v48
	v_cvt_pk_bf16_f32 v35, v35, s0
	v_cvt_pk_bf16_f32 v34, v34, s0
	ds_write_b16 v159, v35 offset:7168
	ds_write_b16 v161, v34 offset:10752
	v_add_f32_e32 v34, v41, v32
	v_exp_f32_e32 v35, v34
	v_and_b32_e32 v39, 0xffff0000, v39
	v_mul_f32_e32 v39, 0x3e13cd3a, v39
	v_lshlrev_b32_e32 v40, 16, v140
	v_mul_f32_e32 v35, v39, v35
	v_exp_f32_e64 v39, -v34
	v_sub_f32_e32 v34, v33, v34
	v_exp_f32_e32 v34, v34
	v_cvt_pk_bf16_f32 v35, v35, s0
	ds_write_b16 v162, v35
	ds_write_b16 v163, v35 offset:3584
	v_mul_f32_e32 v35, v39, v40
	v_mul_f32_e32 v34, v34, v40
	v_cvt_pk_bf16_f32 v35, v35, s0
	v_cvt_pk_bf16_f32 v34, v34, s0
	ds_write_b16 v162, v35 offset:7168
	ds_write_b16 v164, v34 offset:10752
	v_add_f32_e32 v34, v42, v32
	v_exp_f32_e32 v35, v34
	v_lshlrev_b32_e32 v39, 16, v38
	v_mul_f32_e32 v39, 0x3e13cd3a, v39
	v_lshlrev_b32_e32 v40, 16, v136
	v_mul_f32_e32 v35, v39, v35
	v_exp_f32_e64 v39, -v34
	v_sub_f32_e32 v34, v33, v34
	v_exp_f32_e32 v34, v34
	v_cvt_pk_bf16_f32 v35, v35, s0
	ds_write_b16 v165, v35
	ds_write_b16 v166, v35 offset:3584
	v_mul_f32_e32 v35, v39, v40
	v_mul_f32_e32 v34, v34, v40
	v_cvt_pk_bf16_f32 v35, v35, s0
	v_cvt_pk_bf16_f32 v34, v34, s0
	ds_write_b16 v165, v35 offset:7168
	ds_write_b16 v167, v34 offset:10752
	v_add_f32_e32 v34, v43, v32
	v_exp_f32_e32 v35, v34
	v_and_b32_e32 v38, 0xffff0000, v38
	v_mul_f32_e32 v38, 0x3e13cd3a, v38
	v_lshlrev_b32_e32 v39, 16, v138
	v_mul_f32_e32 v35, v38, v35
	v_exp_f32_e64 v38, -v34
	v_sub_f32_e32 v34, v33, v34
	v_exp_f32_e32 v34, v34
	v_cvt_pk_bf16_f32 v35, v35, s0
	ds_write_b16 v168, v35
	ds_write_b16 v169, v35 offset:3584
	v_mul_f32_e32 v35, v38, v39
	v_mul_f32_e32 v34, v34, v39
	v_cvt_pk_bf16_f32 v35, v35, s0
	v_cvt_pk_bf16_f32 v34, v34, s0
	ds_write_b16 v168, v35 offset:7168
	ds_write_b16 v170, v34 offset:10752
	v_add_f32_e32 v34, v44, v32
	v_exp_f32_e32 v35, v34
	v_lshlrev_b32_e32 v38, 16, v37
	v_mul_f32_e32 v38, 0x3e13cd3a, v38
	v_lshlrev_b32_e32 v39, 16, v144
	v_mul_f32_e32 v35, v38, v35
	v_exp_f32_e64 v38, -v34
	v_sub_f32_e32 v34, v33, v34
	v_exp_f32_e32 v34, v34
	v_cvt_pk_bf16_f32 v35, v35, s0
	ds_write_b16 v159, v35 offset:448
	ds_write_b16 v160, v35 offset:4032
	v_mul_f32_e32 v35, v38, v39
	v_mul_f32_e32 v34, v34, v39
	v_cvt_pk_bf16_f32 v35, v35, s0
	v_cvt_pk_bf16_f32 v34, v34, s0
	ds_write_b16 v159, v35 offset:7616
	ds_write_b16 v161, v34 offset:10768
	v_add_f32_e32 v34, v45, v32
	v_exp_f32_e32 v35, v34
	v_and_b32_e32 v37, 0xffff0000, v37
	v_mul_f32_e32 v37, 0x3e13cd3a, v37
	v_lshlrev_b32_e32 v38, 16, v142
	v_mul_f32_e32 v35, v37, v35
	v_exp_f32_e64 v37, -v34
	v_sub_f32_e32 v34, v33, v34
	v_exp_f32_e32 v34, v34
	v_cvt_pk_bf16_f32 v35, v35, s0
	ds_write_b16 v171, v35
	ds_write_b16 v172, v35 offset:3584
	v_mul_f32_e32 v35, v37, v38
	v_mul_f32_e32 v34, v34, v38
	v_cvt_pk_bf16_f32 v35, v35, s0
	v_cvt_pk_bf16_f32 v34, v34, s0
	ds_write_b16 v171, v35 offset:7168
	ds_write_b16 v164, v34 offset:10768
	v_add_f32_e32 v34, v46, v32
	v_exp_f32_e32 v35, v34
	v_lshlrev_b32_e32 v37, 16, v36
	v_mul_f32_e32 v37, 0x3e13cd3a, v37
	v_lshlrev_b32_e32 v38, 16, v137
	v_mul_f32_e32 v35, v37, v35
	v_exp_f32_e64 v37, -v34
	v_sub_f32_e32 v34, v33, v34
	v_exp_f32_e32 v34, v34
	v_cvt_pk_bf16_f32 v35, v35, s0
	ds_write_b16 v173, v35
	ds_write_b16 v174, v35 offset:3584
	v_mul_f32_e32 v35, v37, v38
	v_mul_f32_e32 v34, v34, v38
	v_cvt_pk_bf16_f32 v35, v35, s0
	v_cvt_pk_bf16_f32 v34, v34, s0
	v_add_f32_e32 v32, v47, v32
	ds_write_b16 v173, v35 offset:7168
	ds_write_b16 v167, v34 offset:10768
	v_exp_f32_e32 v34, v32
	v_and_b32_e32 v35, 0xffff0000, v36
	v_mul_f32_e32 v35, 0x3e13cd3a, v35
	v_lshlrev_b32_e32 v36, 16, v139
	v_mul_f32_e32 v34, v35, v34
	v_exp_f32_e64 v35, -v32
	v_sub_f32_e32 v32, v33, v32
	v_exp_f32_e32 v32, v32
	v_cvt_pk_bf16_f32 v34, v34, s0
	v_mul_f32_e32 v33, v35, v36
	v_cvt_pk_bf16_f32 v33, v33, s0
	v_mul_f32_e32 v32, v32, v36
	v_cvt_pk_bf16_f32 v32, v32, s0
	ds_write_b16 v175, v34
	ds_write_b16 v180, v34 offset:3584
	ds_write_b16 v175, v33 offset:7168
	ds_write_b16 v170, v32 offset:10768
.LBB0_543:
	s_or_b64 exec, exec, s[2:3]
	s_waitcnt lgkmcnt(0)
	s_barrier
	s_and_saveexec_b64 s[2:3], vcc
	s_cbranch_execz .Lgla_w3
	ds_read_b128 v[100:103], v145 offset:7168
	ds_read_b128 v[104:107], v145
	ds_read_b128 v[108:111], v145 offset:7200
	ds_read_b128 v[112:115], v145 offset:32
	ds_read_b128 v[116:119], v145 offset:7232
	ds_read_b128 v[120:123], v145 offset:64
	ds_read_b128 v[52:55], v130 offset:15872
	ds_read_b128 v[48:51], v130 offset:15904
	ds_read_b128 v[240:243], v128 offset:23552
	ds_read_b128 v[244:247], v128 offset:23584
	ds_read_b128 v[248:251], v128 offset:23616
	ds_read_b128 v[236:239], v128 offset:23648
	v_cvt_pk_bf16_f32 v204, v0, v1
	v_cvt_pk_bf16_f32 v205, v2, v3
	v_cvt_pk_bf16_f32 v206, v4, v5
	v_cvt_pk_bf16_f32 v207, v6, v7
	v_cvt_pk_bf16_f32 v208, v8, v9
	v_cvt_pk_bf16_f32 v209, v10, v11
	v_cvt_pk_bf16_f32 v210, v12, v13
	v_cvt_pk_bf16_f32 v211, v14, v15
	v_cvt_pk_bf16_f32 v212, v16, v17
	v_cvt_pk_bf16_f32 v213, v18, v19
	v_cvt_pk_bf16_f32 v214, v20, v21
	v_cvt_pk_bf16_f32 v215, v22, v23
	s_waitcnt lgkmcnt(10)
	v_mfma_f32_32x32x16_bf16 v[32:47], v[100:103], v[104:107], 0
	s_waitcnt lgkmcnt(8)
	v_mfma_f32_32x32x16_bf16 v[32:47], v[108:111], v[112:115], v[32:47]
	s_waitcnt lgkmcnt(6)
	v_mfma_f32_32x32x16_bf16 v[32:47], v[116:119], v[120:123], v[32:47]
	ds_read_b128 v[100:103], v128 offset:23680
	ds_read_b128 v[104:107], v128 offset:23712
	ds_read_b128 v[108:111], v128 offset:23744
	ds_read_b128 v[112:115], v128 offset:23776
	ds_read_b128 v[116:119], v131 offset:10752
	ds_read_b128 v[120:123], v131 offset:10784
	s_waitcnt lgkmcnt(6)
	v_pk_mul_f32 v[0:1], v[0:1], v[240:241]
	v_pk_mul_f32 v[2:3], v[2:3], v[242:243]
	v_pk_mul_f32 v[4:5], v[4:5], v[244:245]
	v_pk_mul_f32 v[6:7], v[6:7], v[246:247]
	v_pk_mul_f32 v[8:9], v[8:9], v[248:249]
	v_pk_mul_f32 v[10:11], v[10:11], v[250:251]
	v_pk_mul_f32 v[12:13], v[12:13], v[236:237]
	v_pk_mul_f32 v[14:15], v[14:15], v[238:239]
	ds_read_b128 v[240:243], v131 offset:13312
	ds_read_b128 v[244:247], v131 offset:13344
	ds_read_b128 v[248:251], v145 offset:3584
	ds_read_b128 v[236:239], v145 offset:3616
	s_waitcnt lgkmcnt(5)
	s_nop 0
	v_mfma_f32_32x32x16_bf16 v[0:15], v[116:119], v[52:55], v[0:15]
	v_pk_mul_f32 v[16:17], v[16:17], v[100:101]
	v_pk_mul_f32 v[18:19], v[18:19], v[102:103]
	v_pk_mul_f32 v[20:21], v[20:21], v[104:105]
	v_pk_mul_f32 v[22:23], v[22:23], v[106:107]
	v_pk_mul_f32 v[24:25], v[24:25], v[108:109]
	v_pk_mul_f32 v[26:27], v[26:27], v[110:111]
	v_pk_mul_f32 v[28:29], v[28:29], v[112:113]
	v_pk_mul_f32 v[30:31], v[30:31], v[114:115]
	ds_read_b128 v[100:103], v145 offset:3648
	s_waitcnt lgkmcnt(3)
	s_nop 0
	v_mfma_f32_32x32x16_bf16 v[16:31], v[240:243], v[52:55], v[16:31]
	v_mfma_f32_32x32x16_bf16 v[0:15], v[120:123], v[48:51], v[0:15]
	v_mfma_f32_32x32x16_bf16 v[16:31], v[244:247], v[48:51], v[16:31]
	s_nop 7
	v_cndmask_b32_e64 v32, v32, 0, s[18:19]
	v_cndmask_b32_e64 v33, 0, v33, s[20:21]
	v_cndmask_b32_e64 v34, v34, 0, s[22:23]
	v_cndmask_b32_e64 v35, v35, 0, s[24:25]
	v_cndmask_b32_e64 v36, v36, 0, s[26:27]
	v_cndmask_b32_e64 v37, v37, 0, s[28:29]
	v_cndmask_b32_e64 v38, v38, 0, s[30:31]
	v_cndmask_b32_e64 v39, v39, 0, s[34:35]
	v_cndmask_b32_e64 v40, v40, 0, s[36:37]
	v_cndmask_b32_e64 v41, v41, 0, s[38:39]
	v_cndmask_b32_e64 v42, v42, 0, s[40:41]
	v_cndmask_b32_e64 v43, v43, 0, s[42:43]
	v_cndmask_b32_e64 v44, v44, 0, s[44:45]
	v_cndmask_b32_e64 v45, v45, 0, s[46:47]
	v_cndmask_b32_e64 v46, v46, 0, s[48:49]
	v_cndmask_b32_e64 v47, v47, 0, s[50:51]
	v_cvt_pk_bf16_f32 v32, v32, v33
	v_cvt_pk_bf16_f32 v33, v34, v35
	v_cvt_pk_bf16_f32 v34, v36, v37
	v_cvt_pk_bf16_f32 v35, v38, v39
	v_cvt_pk_bf16_f32 v104, v40, v41
	v_cvt_pk_bf16_f32 v105, v42, v43
	v_cvt_pk_bf16_f32 v106, v44, v45
	v_cvt_pk_bf16_f32 v107, v46, v47
	s_nop 1
	v_mfma_f32_32x32x16_bf16 v[32:47], v[52:55], v[32:35], 0
	v_mfma_f32_32x32x16_bf16 v[32:47], v[48:51], v[104:107], v[32:47]
	s_waitcnt lgkmcnt(0)
	v_mfma_f32_32x32x16_bf16 v[32:47], v[204:207], v[248:251], v[32:47]
	v_mfma_f32_32x32x16_bf16 v[32:47], v[208:211], v[236:239], v[32:47]
	v_mfma_f32_32x32x16_bf16 v[32:47], v[212:215], v[100:103], v[32:47]
	s_nop 15
	global_store_dwordx4 v[134:135], v[32:35], off offset:-64
	global_store_dwordx4 v[134:135], v[36:39], off offset:-32
	global_store_dwordx4 v[134:135], v[40:43], off
	global_store_dwordx4 v[134:135], v[44:47], off offset:32
	s_branch .LBB0_536
.Lgla_w3:
	s_waitcnt vmcnt(0)
	s_branch .LBB0_536
